# P1: V tiles computed with swapped MFMA operands (lane holds 4 consecutive tokens), one 8-byte V^T store per fragment instead of four 2-byte stores
# baseline (speedup 1.0000x reference)
; DI unsigned pack2bf(float a, float b) { const f2_t v = {a, b}; return __builtin_bit_cast(unsigned, __builtin_convertvector(v, bf2_t)); }
; template <class Epi>
; DI void gemm_tile256(const u16* __restrict__ Ag, long lda, const u16* __restrict__ Bg, long ldb, int nk, char* shm, Epi&& epi) {
;   const int tid = RTID, wid = tid >> 6, lane = tid & 63, wr = wid >> 2, wc = wid & 3, fr = lane & 15, fq = lane >> 4;
;   f32x4 acc[8][4];
; #pragma unroll
;   for (int m = 0; m < 8; ++m)
; #pragma unroll
;     for (int n = 0; n < 4; ++n) acc[m][n] = f32x4{0.f, 0.f, 0.f, 0.f};
;   const int q0 = tid, q1 = 512 + tid;
;   const int r0 = q0 >> 2, r1 = q1 >> 2, c0 = (q0 & 3) ^ ((r0 >> 2) & 3), c1 = (q1 & 3) ^ ((r1 >> 2) & 3);
;   const u16* a0 = Ag + (long)r0 * lda + c0 * 8; const u16* a1 = Ag + (long)r1 * lda + c1 * 8;
;   const u16* b0 = Bg + (long)r0 * ldb + c0 * 8; const u16* b1 = Bg + (long)r1 * ldb + c1 * 8;
;   auto stage = [&](int j) {
;     char* SA = shm + (j & 3) * 32768; char* SB = SA + 16384;
;     __builtin_amdgcn_global_load_lds((const unsigned*)(a0 + j * 32), (__attribute__((address_space(3))) unsigned*)(SA + q0 * 16), 16, 0, 0);
;     __builtin_amdgcn_global_load_lds((const unsigned*)(a1 + j * 32), (__attribute__((address_space(3))) unsigned*)(SA + q1 * 16), 16, 0, 0);
;     __builtin_amdgcn_global_load_lds((const unsigned*)(b0 + j * 32), (__attribute__((address_space(3))) unsigned*)(SB + q0 * 16), 16, 0, 0);
;     __builtin_amdgcn_global_load_lds((const unsigned*)(b1 + j * 32), (__attribute__((address_space(3))) unsigned*)(SB + q1 * 16), 16, 0, 0);
;   };
;   __syncthreads();
;   stage(0);
;   if (nk > 1) stage(1);
;   if (nk > 2) stage(2);
; DI void phase1(const Params& P, char* smem) {
;     ...
;   for (int q = RBLK >> 3; q < 128; q += RGRID >> 3) {
;     const int brow = q * 256, bcol = (RBLK & 7) * 256;
;     gemm_tile256(xb + (long)brow * 1024, 1024, WinT + (long)bcol * 1024, 1024, 32, smem, [&](int row, int col0, f32x4 v) {
;       const int r = brow + row, c = bcol + col0;
;       const uint2 pk = make_uint2(pack2bf(v[0], v[1]), pack2bf(v[2], v[3]));
;       if (bcol < 512) {
.LBB0_107:
	v_lshl_add_u64 v[176:177], v[138:139], 0, 64
	v_lshl_add_u64 v[178:179], v[140:141], 0, 64
	v_lshl_add_u64 v[180:181], v[138:139], 0, s[0:1]
	v_lshl_add_u64 v[182:183], v[140:141], 0, s[0:1]
	s_lshl_b32 s30, s27, 8
	s_ashr_i32 s29, s28, 31
	s_ashr_i32 s31, s30, 31
	s_lshl_b64 s[6:7], s[28:29], 11
	s_lshl_b64 s[4:5], s[30:31], 11
	s_add_u32 s4, s54, s4
	s_addc_u32 s5, s55, s5
	v_add_u32_e32 v6, 0, v209
	v_lshl_add_u64 v[0:1], s[4:5], 0, v[132:133]
	v_lshl_add_u64 v[2:3], s[4:5], 0, v[136:137]
	v_readfirstlane_b32 s4, v6
	v_add_u32_e32 v7, 0, v131
	v_lshl_add_u64 v[0:1], v[0:1], 0, v[134:135]
	s_mov_b32 m0, s4
	v_readfirstlane_b32 s4, v7
	v_add_u32_e32 v4, 0x4000, v6
	v_lshl_add_u64 v[2:3], v[2:3], 0, v[134:135]
	s_barrier
	global_load_lds_dwordx4 v[0:1], off
	s_mov_b32 m0, s4
	v_readfirstlane_b32 s4, v4
	v_add_u32_e32 v4, 0x4000, v7
	global_load_lds_dwordx4 v[2:3], off
	s_mov_b32 m0, s4
	v_readfirstlane_b32 s4, v4
	v_add_u32_e32 v8, 0x8000, v6
	global_load_lds_dwordx4 v[138:139], off
	s_mov_b32 m0, s4
	v_readfirstlane_b32 s4, v8
	v_add_u32_e32 v8, 0x8000, v7
	global_load_lds_dwordx4 v[140:141], off
	v_lshl_add_u64 v[4:5], v[0:1], 0, 64
	s_mov_b32 m0, s4
	v_readfirstlane_b32 s4, v8
	global_load_lds_dwordx4 v[4:5], off
	v_lshl_add_u64 v[4:5], v[2:3], 0, 64
	s_mov_b32 m0, s4
	v_lshl_add_u64 v[0:1], v[0:1], 0, s[0:1]
	global_load_lds_dwordx4 v[4:5], off
	v_add_u32_e32 v4, 0xc000, v6
	s_mov_b32 s8, 0x18000
	v_readfirstlane_b32 s4, v4
	v_add_u32_e32 v4, 0xc000, v7
	s_mov_b32 m0, s4
	v_readfirstlane_b32 s4, v4
	v_add_u32_e32 v4, s2, v209
	global_load_lds_dwordx4 v[176:177], off
	s_mov_b32 m0, s4
	v_readfirstlane_b32 s4, v4
	global_load_lds_dwordx4 v[178:179], off
	s_mov_b32 m0, s4
	v_mov_b32_e32 v4, 0
	global_load_lds_dwordx4 v[0:1], off
	v_lshl_add_u64 v[0:1], v[2:3], 0, s[0:1]
	v_add_u32_e32 v2, s2, v131
	v_mov_b32_e32 v3, v135
	v_readfirstlane_b32 s4, v2
	s_mov_b32 m0, s4
	v_mov_b32_e32 v2, v135
	global_load_lds_dwordx4 v[0:1], off
	v_add_u32_e32 v0, s15, v209
	v_mov_b32_e32 v1, v135
	v_readfirstlane_b32 s4, v0
	v_add_u32_e32 v0, s15, v131
	s_mov_b32 m0, s4
	v_readfirstlane_b32 s4, v0
	global_load_lds_dwordx4 v[180:181], off
	s_mov_b32 m0, s4
	s_mov_b64 s[4:5], 0
	global_load_lds_dwordx4 v[182:183], off
	v_mov_b32_e32 v0, 0
	v_mov_b32_e32 v5, v135
	v_mov_b32_e32 v6, v135
	v_mov_b32_e32 v7, v135
	v_mov_b32_e32 v8, 0
	v_mov_b32_e32 v9, v135
	v_mov_b32_e32 v10, v135
	v_mov_b32_e32 v11, v135
	v_mov_b32_e32 v12, 0
	v_mov_b32_e32 v13, v135
	v_mov_b32_e32 v14, v135
	v_mov_b32_e32 v15, v135
	v_mov_b32_e32 v16, 0
	v_mov_b32_e32 v17, v135
	v_mov_b32_e32 v18, v135
	v_mov_b32_e32 v19, v135
	v_mov_b32_e32 v20, 0
	v_mov_b32_e32 v21, v135
	v_mov_b32_e32 v22, v135
	v_mov_b32_e32 v23, v135
	v_mov_b32_e32 v24, 0
	v_mov_b32_e32 v25, v135
	v_mov_b32_e32 v26, v135
	v_mov_b32_e32 v27, v135
	v_mov_b32_e32 v28, 0
	v_mov_b32_e32 v29, v135
	v_mov_b32_e32 v30, v135
	v_mov_b32_e32 v31, v135
	v_mov_b32_e32 v32, 0
	v_mov_b32_e32 v33, v135
	v_mov_b32_e32 v34, v135
	v_mov_b32_e32 v35, v135
	v_mov_b32_e32 v36, 0
	v_mov_b32_e32 v37, v135
	v_mov_b32_e32 v38, v135
	v_mov_b32_e32 v39, v135
	v_mov_b32_e32 v40, 0
	v_mov_b32_e32 v41, v135
	v_mov_b32_e32 v42, v135
	v_mov_b32_e32 v43, v135
	v_mov_b32_e32 v44, 0
	v_mov_b32_e32 v45, v135
	v_mov_b32_e32 v46, v135
	v_mov_b32_e32 v47, v135
	v_mov_b32_e32 v48, 0
	v_mov_b32_e32 v49, v135
	v_mov_b32_e32 v50, v135
	v_mov_b32_e32 v51, v135
	v_mov_b32_e32 v52, 0
	v_mov_b32_e32 v53, v135
	v_mov_b32_e32 v54, v135
	v_mov_b32_e32 v55, v135
	v_mov_b32_e32 v56, 0
	v_mov_b32_e32 v57, v135
	v_mov_b32_e32 v58, v135
	v_mov_b32_e32 v59, v135
	v_mov_b32_e32 v60, 0
	v_mov_b32_e32 v61, v135
	v_mov_b32_e32 v62, v135
	v_mov_b32_e32 v63, v135
	v_mov_b32_e32 v64, 0
	v_mov_b32_e32 v65, v135
	v_mov_b32_e32 v66, v135
	v_mov_b32_e32 v67, v135
	v_mov_b32_e32 v68, 0
	v_mov_b32_e32 v69, v135
	v_mov_b32_e32 v70, v135
	v_mov_b32_e32 v71, v135
	v_mov_b32_e32 v72, 0
	v_mov_b32_e32 v73, v135
	v_mov_b32_e32 v74, v135
	v_mov_b32_e32 v75, v135
	v_mov_b32_e32 v76, 0
	v_mov_b32_e32 v77, v135
	v_mov_b32_e32 v78, v135
	v_mov_b32_e32 v79, v135
	v_mov_b32_e32 v80, 0
	v_mov_b32_e32 v81, v135
	v_mov_b32_e32 v82, v135
	v_mov_b32_e32 v83, v135
	v_mov_b32_e32 v84, 0
	v_mov_b32_e32 v85, v135
	v_mov_b32_e32 v86, v135
	v_mov_b32_e32 v87, v135
	v_mov_b32_e32 v88, 0
	v_mov_b32_e32 v89, v135
	v_mov_b32_e32 v90, v135
	v_mov_b32_e32 v91, v135
	v_mov_b32_e32 v92, 0
	v_mov_b32_e32 v93, v135
	v_mov_b32_e32 v94, v135
	v_mov_b32_e32 v95, v135
	v_mov_b32_e32 v96, 0
	v_mov_b32_e32 v97, v135
	v_mov_b32_e32 v98, v135
	v_mov_b32_e32 v99, v135
	v_mov_b32_e32 v100, 0
	v_mov_b32_e32 v101, v135
	v_mov_b32_e32 v102, v135
	v_mov_b32_e32 v103, v135
	v_mov_b32_e32 v104, 0
	v_mov_b32_e32 v105, v135
	v_mov_b32_e32 v106, v135
	v_mov_b32_e32 v107, v135
	v_mov_b32_e32 v108, 0
	v_mov_b32_e32 v109, v135
	v_mov_b32_e32 v110, v135
	v_mov_b32_e32 v111, v135
	v_mov_b32_e32 v112, 0
	v_mov_b32_e32 v113, v135
	v_mov_b32_e32 v114, v135
	v_mov_b32_e32 v115, v135
	v_mov_b32_e32 v116, 0
	v_mov_b32_e32 v117, v135
	v_mov_b32_e32 v118, v135
	v_mov_b32_e32 v119, v135
	v_mov_b32_e32 v120, 0
	v_mov_b32_e32 v121, v135
	v_mov_b32_e32 v122, v135
	v_mov_b32_e32 v123, v135
	v_mov_b32_e32 v124, 0
	v_mov_b32_e32 v125, v135
	v_mov_b32_e32 v126, v135
	v_mov_b32_e32 v127, v135
	v_lshl_add_u64 v[184:185], v[168:169], 0, s[6:7]
	v_lshl_add_u64 v[186:187], v[170:171], 0, s[6:7]
	v_readfirstlane_b32 s7, v209
	s_mov_b32 s8, 0
	s_mov_b64 s[4:5], 0
	s_and_b64 vcc, exec, s[24:25]
	s_cbranch_vccz .Lgemm_p1_n
	s_waitcnt vmcnt(8)
	s_barrier
	v_add3_u32 v252, v205, v147, s8
	v_add3_u32 v215, v205, v151, s8
	s_nop 0
	ds_read_b128 v[216:219], v252 offset:16384
	ds_read_b128 v[220:223], v252 offset:17408
	ds_read_b128 v[232:235], v252 offset:18432
	ds_read_b128 v[236:239], v252 offset:19456
	ds_read_b128 v[224:227], v215
	ds_read_b128 v[228:231], v215 offset:1024
; template <class Epi>
; DI void gemm_tile256(const u16* __restrict__ Ag, long lda, const u16* __restrict__ Bg, long ldb, int nk, char* shm, Epi&& epi) {
;     ...
;   for (int i = 0; i < nk; ++i) {
;     if (i + 2 < nk) asm volatile("s_waitcnt vmcnt(8)" ::: "memory");
;     else if (i + 1 < nk) asm volatile("s_waitcnt vmcnt(4)" ::: "memory");
;     else asm volatile("s_waitcnt vmcnt(0)" ::: "memory");
;     __builtin_amdgcn_s_barrier();
;     const char* SA = shm + (i & 3) * 32768; const char* SB = SA + 16384;
;     bf16x8 At[8], Bt[4];
; #pragma unroll
;     for (int n = 0; n < 4; ++n) { const int rb = wc * 64 + n * 16 + fr; Bt[n] = *reinterpret_cast<const bf16x8*>(SB + rb * 64 + ((fq ^ ((rb >> 2) & 3)) * 16)); }
; #pragma unroll
;     for (int m = 0; m < 8; ++m) { const int ra = wr * 128 + m * 16 + fr; At[m] = *reinterpret_cast<const bf16x8*>(SA + ra * 64 + ((fq ^ ((ra >> 2) & 3)) * 16)); }
;     if (i + 3 < nk) stage(i + 3);
; #pragma unroll
;     for (int m = 0; m < 8; ++m)
; #pragma unroll
;       for (int n = 0; n < 4; ++n) acc[m][n] = __builtin_amdgcn_mfma_f32_16x16x32_bf16(Bt[n], At[m], acc[m][n], 0, 0, 0);
;   }
.Lgemm_p1_kloopv:
	s_add_i32 s6, s8, 0x18000
	s_and_b32 s6, s6, 0x18000
	s_add_i32 s9, s6, s7
	ds_read_b128 v[180:183], v215 offset:2048
	ds_read_b128 v[210:213], v215 offset:3072
	s_waitcnt lgkmcnt(2)
	v_mfma_f32_16x16x32_bf16 v[124:127], v[224:227], v[216:219], v[124:127]
	v_lshl_add_u64 v[206:207], v[184:185], 0, s[4:5]
	v_mfma_f32_16x16x32_bf16 v[120:123], v[224:227], v[220:223], v[120:123]
	s_mov_b32 m0, s9
	v_mfma_f32_16x16x32_bf16 v[116:119], v[224:227], v[232:235], v[116:119]
	s_add_i32 s9, s9, 0x2000
	v_mfma_f32_16x16x32_bf16 v[112:115], v[224:227], v[236:239], v[112:115]
	global_load_lds_dwordx4 v[206:207], off
	v_mfma_f32_16x16x32_bf16 v[108:111], v[228:231], v[216:219], v[108:111]
	v_mfma_f32_16x16x32_bf16 v[104:107], v[228:231], v[220:223], v[104:107]
	v_mfma_f32_16x16x32_bf16 v[100:103], v[228:231], v[232:235], v[100:103]
	v_mfma_f32_16x16x32_bf16 v[96:99], v[228:231], v[236:239], v[96:99]
	ds_read_b128 v[224:227], v215 offset:4096
	ds_read_b128 v[228:231], v215 offset:5120
	s_waitcnt lgkmcnt(2)
	v_mfma_f32_16x16x32_bf16 v[92:95], v[180:183], v[216:219], v[92:95]
	v_lshl_add_u64 v[206:207], v[186:187], 0, s[4:5]
	v_mfma_f32_16x16x32_bf16 v[88:91], v[180:183], v[220:223], v[88:91]
	s_mov_b32 m0, s9
	v_mfma_f32_16x16x32_bf16 v[84:87], v[180:183], v[232:235], v[84:87]
	s_add_i32 s9, s9, 0x2000
	v_mfma_f32_16x16x32_bf16 v[80:83], v[180:183], v[236:239], v[80:83]
	global_load_lds_dwordx4 v[206:207], off
	v_mfma_f32_16x16x32_bf16 v[76:79], v[210:213], v[216:219], v[76:79]
	v_mfma_f32_16x16x32_bf16 v[72:75], v[210:213], v[220:223], v[72:75]
	v_mfma_f32_16x16x32_bf16 v[68:71], v[210:213], v[232:235], v[68:71]
	v_mfma_f32_16x16x32_bf16 v[64:67], v[210:213], v[236:239], v[64:67]
	ds_read_b128 v[180:183], v215 offset:6144
	ds_read_b128 v[210:213], v215 offset:7168
	s_waitcnt lgkmcnt(2)
	v_mfma_f32_16x16x32_bf16 v[60:63], v[224:227], v[216:219], v[60:63]
	v_lshl_add_u64 v[206:207], v[172:173], 0, s[4:5]
	v_mfma_f32_16x16x32_bf16 v[56:59], v[224:227], v[220:223], v[56:59]
	s_mov_b32 m0, s9
	v_mfma_f32_16x16x32_bf16 v[52:55], v[224:227], v[232:235], v[52:55]
	s_add_i32 s9, s9, 0x2000
	v_mfma_f32_16x16x32_bf16 v[48:51], v[224:227], v[236:239], v[48:51]
	global_load_lds_dwordx4 v[206:207], off
	v_mfma_f32_16x16x32_bf16 v[44:47], v[228:231], v[216:219], v[44:47]
	v_mfma_f32_16x16x32_bf16 v[40:43], v[228:231], v[220:223], v[40:43]
	v_mfma_f32_16x16x32_bf16 v[36:39], v[228:231], v[232:235], v[36:39]
	v_mfma_f32_16x16x32_bf16 v[32:35], v[228:231], v[236:239], v[32:35]
	s_add_i32 s8, s8, 0x8000
	s_and_b32 s8, s8, 0x18000
	s_waitcnt vmcnt(7) lgkmcnt(0)
	s_barrier
	v_add3_u32 v252, v205, v147, s8
	v_add3_u32 v215, v205, v151, s8
	s_nop 0
	ds_read_b128 v[240:243], v252 offset:16384
	ds_read_b128 v[244:247], v252 offset:17408
	ds_read_b128 v[248:251], v252 offset:18432
	ds_read_b128 v[176:179], v252 offset:19456
	ds_read_b128 v[224:227], v215
	ds_read_b128 v[228:231], v215 offset:1024
	v_mfma_f32_16x16x32_bf16 v[28:31], v[180:183], v[216:219], v[28:31]
	v_lshl_add_u64 v[206:207], v[174:175], 0, s[4:5]
	v_mfma_f32_16x16x32_bf16 v[24:27], v[180:183], v[220:223], v[24:27]
	s_mov_b32 m0, s9
	v_mfma_f32_16x16x32_bf16 v[20:23], v[180:183], v[232:235], v[20:23]
	s_add_i32 s9, s9, 0x2000
	v_mfma_f32_16x16x32_bf16 v[16:19], v[180:183], v[236:239], v[16:19]
	global_load_lds_dwordx4 v[206:207], off
	v_mfma_f32_16x16x32_bf16 v[12:15], v[210:213], v[216:219], v[12:15]
	s_add_u32 s4, s4, 64
	v_mfma_f32_16x16x32_bf16 v[8:11], v[210:213], v[220:223], v[8:11]
	s_addc_u32 s5, s5, 0
	v_mfma_f32_16x16x32_bf16 v[4:7], v[210:213], v[232:235], v[4:7]
	v_mfma_f32_16x16x32_bf16 v[0:3], v[210:213], v[236:239], v[0:3]
	s_add_i32 s6, s8, 0x18000
	s_and_b32 s6, s6, 0x18000
	s_add_i32 s9, s6, s7
	ds_read_b128 v[180:183], v215 offset:2048
	ds_read_b128 v[210:213], v215 offset:3072
	s_waitcnt lgkmcnt(2)
	v_mfma_f32_16x16x32_bf16 v[124:127], v[224:227], v[240:243], v[124:127]
	v_lshl_add_u64 v[206:207], v[184:185], 0, s[4:5]
	v_mfma_f32_16x16x32_bf16 v[120:123], v[224:227], v[244:247], v[120:123]
	s_mov_b32 m0, s9
	v_mfma_f32_16x16x32_bf16 v[116:119], v[224:227], v[248:251], v[116:119]
	s_add_i32 s9, s9, 0x2000
	v_mfma_f32_16x16x32_bf16 v[112:115], v[224:227], v[176:179], v[112:115]
	global_load_lds_dwordx4 v[206:207], off
	v_mfma_f32_16x16x32_bf16 v[108:111], v[228:231], v[240:243], v[108:111]
	v_mfma_f32_16x16x32_bf16 v[104:107], v[228:231], v[244:247], v[104:107]
	v_mfma_f32_16x16x32_bf16 v[100:103], v[228:231], v[248:251], v[100:103]
	v_mfma_f32_16x16x32_bf16 v[96:99], v[228:231], v[176:179], v[96:99]
	ds_read_b128 v[224:227], v215 offset:4096
	ds_read_b128 v[228:231], v215 offset:5120
	s_waitcnt lgkmcnt(2)
	v_mfma_f32_16x16x32_bf16 v[92:95], v[180:183], v[240:243], v[92:95]
	v_lshl_add_u64 v[206:207], v[186:187], 0, s[4:5]
	v_mfma_f32_16x16x32_bf16 v[88:91], v[180:183], v[244:247], v[88:91]
	s_mov_b32 m0, s9
	v_mfma_f32_16x16x32_bf16 v[84:87], v[180:183], v[248:251], v[84:87]
	s_add_i32 s9, s9, 0x2000
	v_mfma_f32_16x16x32_bf16 v[80:83], v[180:183], v[176:179], v[80:83]
	global_load_lds_dwordx4 v[206:207], off
	v_mfma_f32_16x16x32_bf16 v[76:79], v[210:213], v[240:243], v[76:79]
	v_mfma_f32_16x16x32_bf16 v[72:75], v[210:213], v[244:247], v[72:75]
	v_mfma_f32_16x16x32_bf16 v[68:71], v[210:213], v[248:251], v[68:71]
	v_mfma_f32_16x16x32_bf16 v[64:67], v[210:213], v[176:179], v[64:67]
	ds_read_b128 v[180:183], v215 offset:6144
	ds_read_b128 v[210:213], v215 offset:7168
	s_waitcnt lgkmcnt(2)
	v_mfma_f32_16x16x32_bf16 v[60:63], v[224:227], v[240:243], v[60:63]
	v_lshl_add_u64 v[206:207], v[172:173], 0, s[4:5]
	v_mfma_f32_16x16x32_bf16 v[56:59], v[224:227], v[244:247], v[56:59]
	s_mov_b32 m0, s9
	v_mfma_f32_16x16x32_bf16 v[52:55], v[224:227], v[248:251], v[52:55]
	s_add_i32 s9, s9, 0x2000
	v_mfma_f32_16x16x32_bf16 v[48:51], v[224:227], v[176:179], v[48:51]
	global_load_lds_dwordx4 v[206:207], off
	v_mfma_f32_16x16x32_bf16 v[44:47], v[228:231], v[240:243], v[44:47]
	v_mfma_f32_16x16x32_bf16 v[40:43], v[228:231], v[244:247], v[40:43]
	v_mfma_f32_16x16x32_bf16 v[36:39], v[228:231], v[248:251], v[36:39]
	v_mfma_f32_16x16x32_bf16 v[32:35], v[228:231], v[176:179], v[32:35]
	s_add_i32 s8, s8, 0x8000
	s_and_b32 s8, s8, 0x18000
	s_waitcnt vmcnt(7) lgkmcnt(0)
	s_barrier
; template <class Epi>
; DI void gemm_tile256(const u16* __restrict__ Ag, long lda, const u16* __restrict__ Bg, long ldb, int nk, char* shm, Epi&& epi) {
;     ...
;   for (int i = 0; i < nk; ++i) {
;     if (i + 2 < nk) asm volatile("s_waitcnt vmcnt(8)" ::: "memory");
;     else if (i + 1 < nk) asm volatile("s_waitcnt vmcnt(4)" ::: "memory");
;     else asm volatile("s_waitcnt vmcnt(0)" ::: "memory");
;     __builtin_amdgcn_s_barrier();
;     const char* SA = shm + (i & 3) * 32768; const char* SB = SA + 16384;
;     bf16x8 At[8], Bt[4];
; #pragma unroll
;     for (int n = 0; n < 4; ++n) { const int rb = wc * 64 + n * 16 + fr; Bt[n] = *reinterpret_cast<const bf16x8*>(SB + rb * 64 + ((fq ^ ((rb >> 2) & 3)) * 16)); }
; #pragma unroll
;     for (int m = 0; m < 8; ++m) { const int ra = wr * 128 + m * 16 + fr; At[m] = *reinterpret_cast<const bf16x8*>(SA + ra * 64 + ((fq ^ ((ra >> 2) & 3)) * 16)); }
;     if (i + 3 < nk) stage(i + 3);
; #pragma unroll
;     for (int m = 0; m < 8; ++m)
; #pragma unroll
;       for (int n = 0; n < 4; ++n) acc[m][n] = __builtin_amdgcn_mfma_f32_16x16x32_bf16(Bt[n], At[m], acc[m][n], 0, 0, 0);
;   }
	v_add3_u32 v252, v205, v147, s8
	v_add3_u32 v215, v205, v151, s8
	s_nop 0
	ds_read_b128 v[216:219], v252 offset:16384
	ds_read_b128 v[220:223], v252 offset:17408
	ds_read_b128 v[232:235], v252 offset:18432
	ds_read_b128 v[236:239], v252 offset:19456
	ds_read_b128 v[224:227], v215
	ds_read_b128 v[228:231], v215 offset:1024
	v_mfma_f32_16x16x32_bf16 v[28:31], v[180:183], v[240:243], v[28:31]
	v_lshl_add_u64 v[206:207], v[174:175], 0, s[4:5]
	v_mfma_f32_16x16x32_bf16 v[24:27], v[180:183], v[244:247], v[24:27]
	s_mov_b32 m0, s9
	v_mfma_f32_16x16x32_bf16 v[20:23], v[180:183], v[248:251], v[20:23]
	s_add_i32 s9, s9, 0x2000
	v_mfma_f32_16x16x32_bf16 v[16:19], v[180:183], v[176:179], v[16:19]
	global_load_lds_dwordx4 v[206:207], off
	v_mfma_f32_16x16x32_bf16 v[12:15], v[210:213], v[240:243], v[12:15]
	s_add_u32 s4, s4, 64
	v_mfma_f32_16x16x32_bf16 v[8:11], v[210:213], v[244:247], v[8:11]
	s_addc_u32 s5, s5, 0
	v_mfma_f32_16x16x32_bf16 v[4:7], v[210:213], v[248:251], v[4:7]
	v_mfma_f32_16x16x32_bf16 v[0:3], v[210:213], v[176:179], v[0:3]
	s_cmpk_lg_i32 s4, 0x700
	s_cbranch_scc1 .Lgemm_p1_kloopv
	s_add_i32 s6, s8, 0x18000
	s_and_b32 s6, s6, 0x18000
	s_add_i32 s9, s6, s7
	ds_read_b128 v[180:183], v215 offset:2048
	ds_read_b128 v[210:213], v215 offset:3072
	s_waitcnt lgkmcnt(2)
	v_mfma_f32_16x16x32_bf16 v[124:127], v[224:227], v[216:219], v[124:127]
	v_lshl_add_u64 v[206:207], v[184:185], 0, s[4:5]
	v_mfma_f32_16x16x32_bf16 v[120:123], v[224:227], v[220:223], v[120:123]
	s_mov_b32 m0, s9
	v_mfma_f32_16x16x32_bf16 v[116:119], v[224:227], v[232:235], v[116:119]
	s_add_i32 s9, s9, 0x2000
	v_mfma_f32_16x16x32_bf16 v[112:115], v[224:227], v[236:239], v[112:115]
	global_load_lds_dwordx4 v[206:207], off
	v_mfma_f32_16x16x32_bf16 v[108:111], v[228:231], v[216:219], v[108:111]
	v_mfma_f32_16x16x32_bf16 v[104:107], v[228:231], v[220:223], v[104:107]
	v_mfma_f32_16x16x32_bf16 v[100:103], v[228:231], v[232:235], v[100:103]
	v_mfma_f32_16x16x32_bf16 v[96:99], v[228:231], v[236:239], v[96:99]
	ds_read_b128 v[224:227], v215 offset:4096
	ds_read_b128 v[228:231], v215 offset:5120
	s_waitcnt lgkmcnt(2)
	v_mfma_f32_16x16x32_bf16 v[92:95], v[180:183], v[216:219], v[92:95]
	v_lshl_add_u64 v[206:207], v[186:187], 0, s[4:5]
	v_mfma_f32_16x16x32_bf16 v[88:91], v[180:183], v[220:223], v[88:91]
	s_mov_b32 m0, s9
	v_mfma_f32_16x16x32_bf16 v[84:87], v[180:183], v[232:235], v[84:87]
	s_add_i32 s9, s9, 0x2000
	v_mfma_f32_16x16x32_bf16 v[80:83], v[180:183], v[236:239], v[80:83]
	global_load_lds_dwordx4 v[206:207], off
	v_mfma_f32_16x16x32_bf16 v[76:79], v[210:213], v[216:219], v[76:79]
	v_mfma_f32_16x16x32_bf16 v[72:75], v[210:213], v[220:223], v[72:75]
	v_mfma_f32_16x16x32_bf16 v[68:71], v[210:213], v[232:235], v[68:71]
	v_mfma_f32_16x16x32_bf16 v[64:67], v[210:213], v[236:239], v[64:67]
	ds_read_b128 v[180:183], v215 offset:6144
	ds_read_b128 v[210:213], v215 offset:7168
	s_waitcnt lgkmcnt(2)
	v_mfma_f32_16x16x32_bf16 v[60:63], v[224:227], v[216:219], v[60:63]
	v_lshl_add_u64 v[206:207], v[172:173], 0, s[4:5]
	v_mfma_f32_16x16x32_bf16 v[56:59], v[224:227], v[220:223], v[56:59]
	s_mov_b32 m0, s9
	v_mfma_f32_16x16x32_bf16 v[52:55], v[224:227], v[232:235], v[52:55]
	s_add_i32 s9, s9, 0x2000
	v_mfma_f32_16x16x32_bf16 v[48:51], v[224:227], v[236:239], v[48:51]
	global_load_lds_dwordx4 v[206:207], off
	v_mfma_f32_16x16x32_bf16 v[44:47], v[228:231], v[216:219], v[44:47]
	v_mfma_f32_16x16x32_bf16 v[40:43], v[228:231], v[220:223], v[40:43]
	v_mfma_f32_16x16x32_bf16 v[36:39], v[228:231], v[232:235], v[36:39]
	v_mfma_f32_16x16x32_bf16 v[32:35], v[228:231], v[236:239], v[32:35]
	s_add_i32 s8, s8, 0x8000
	s_and_b32 s8, s8, 0x18000
	s_waitcnt vmcnt(7) lgkmcnt(0)
	s_barrier
	v_add3_u32 v252, v205, v147, s8
	v_add3_u32 v215, v205, v151, s8
	s_nop 0
	ds_read_b128 v[240:243], v252 offset:16384
	ds_read_b128 v[244:247], v252 offset:17408
	ds_read_b128 v[248:251], v252 offset:18432
	ds_read_b128 v[176:179], v252 offset:19456
	ds_read_b128 v[224:227], v215
	ds_read_b128 v[228:231], v215 offset:1024
	v_mfma_f32_16x16x32_bf16 v[28:31], v[180:183], v[216:219], v[28:31]
	v_lshl_add_u64 v[206:207], v[174:175], 0, s[4:5]
	v_mfma_f32_16x16x32_bf16 v[24:27], v[180:183], v[220:223], v[24:27]
	s_mov_b32 m0, s9
	v_mfma_f32_16x16x32_bf16 v[20:23], v[180:183], v[232:235], v[20:23]
	s_add_i32 s9, s9, 0x2000
	v_mfma_f32_16x16x32_bf16 v[16:19], v[180:183], v[236:239], v[16:19]
	global_load_lds_dwordx4 v[206:207], off
	v_mfma_f32_16x16x32_bf16 v[12:15], v[210:213], v[216:219], v[12:15]
	s_add_u32 s4, s4, 64
	v_mfma_f32_16x16x32_bf16 v[8:11], v[210:213], v[220:223], v[8:11]
	s_addc_u32 s5, s5, 0
	v_mfma_f32_16x16x32_bf16 v[4:7], v[210:213], v[232:235], v[4:7]
	v_mfma_f32_16x16x32_bf16 v[0:3], v[210:213], v[236:239], v[0:3]
	ds_read_b128 v[180:183], v215 offset:2048
	ds_read_b128 v[210:213], v215 offset:3072
	s_waitcnt lgkmcnt(2)
	v_mfma_f32_16x16x32_bf16 v[124:127], v[224:227], v[240:243], v[124:127]
	v_mfma_f32_16x16x32_bf16 v[120:123], v[224:227], v[244:247], v[120:123]
	v_mfma_f32_16x16x32_bf16 v[116:119], v[224:227], v[248:251], v[116:119]
	v_mfma_f32_16x16x32_bf16 v[112:115], v[224:227], v[176:179], v[112:115]
	v_mfma_f32_16x16x32_bf16 v[108:111], v[228:231], v[240:243], v[108:111]
	v_mfma_f32_16x16x32_bf16 v[104:107], v[228:231], v[244:247], v[104:107]
	v_mfma_f32_16x16x32_bf16 v[100:103], v[228:231], v[248:251], v[100:103]
	v_mfma_f32_16x16x32_bf16 v[96:99], v[228:231], v[176:179], v[96:99]
	ds_read_b128 v[224:227], v215 offset:4096
	ds_read_b128 v[228:231], v215 offset:5120
	s_waitcnt lgkmcnt(2)
	v_mfma_f32_16x16x32_bf16 v[92:95], v[180:183], v[240:243], v[92:95]
	v_mfma_f32_16x16x32_bf16 v[88:91], v[180:183], v[244:247], v[88:91]
	v_mfma_f32_16x16x32_bf16 v[84:87], v[180:183], v[248:251], v[84:87]
	v_mfma_f32_16x16x32_bf16 v[80:83], v[180:183], v[176:179], v[80:83]
	v_mfma_f32_16x16x32_bf16 v[76:79], v[210:213], v[240:243], v[76:79]
	v_mfma_f32_16x16x32_bf16 v[72:75], v[210:213], v[244:247], v[72:75]
	v_mfma_f32_16x16x32_bf16 v[68:71], v[210:213], v[248:251], v[68:71]
	v_mfma_f32_16x16x32_bf16 v[64:67], v[210:213], v[176:179], v[64:67]
	ds_read_b128 v[180:183], v215 offset:6144
	ds_read_b128 v[210:213], v215 offset:7168
	s_waitcnt lgkmcnt(2)
	v_mfma_f32_16x16x32_bf16 v[60:63], v[224:227], v[240:243], v[60:63]
	v_mfma_f32_16x16x32_bf16 v[56:59], v[224:227], v[244:247], v[56:59]
	v_mfma_f32_16x16x32_bf16 v[52:55], v[224:227], v[248:251], v[52:55]
	v_mfma_f32_16x16x32_bf16 v[48:51], v[224:227], v[176:179], v[48:51]
	v_mfma_f32_16x16x32_bf16 v[44:47], v[228:231], v[240:243], v[44:47]
	v_mfma_f32_16x16x32_bf16 v[40:43], v[228:231], v[244:247], v[40:43]
	v_mfma_f32_16x16x32_bf16 v[36:39], v[228:231], v[248:251], v[36:39]
	v_mfma_f32_16x16x32_bf16 v[32:35], v[228:231], v[176:179], v[32:35]
	s_add_i32 s8, s8, 0x8000
	s_and_b32 s8, s8, 0x18000
	s_waitcnt vmcnt(4) lgkmcnt(0)
	s_barrier
; template <class Epi>
; DI void gemm_tile256(const u16* __restrict__ Ag, long lda, const u16* __restrict__ Bg, long ldb, int nk, char* shm, Epi&& epi) {
;     ...
;   for (int i = 0; i < nk; ++i) {
;     if (i + 2 < nk) asm volatile("s_waitcnt vmcnt(8)" ::: "memory");
;     else if (i + 1 < nk) asm volatile("s_waitcnt vmcnt(4)" ::: "memory");
;     else asm volatile("s_waitcnt vmcnt(0)" ::: "memory");
;     __builtin_amdgcn_s_barrier();
;     const char* SA = shm + (i & 3) * 32768; const char* SB = SA + 16384;
;     bf16x8 At[8], Bt[4];
; #pragma unroll
;     for (int n = 0; n < 4; ++n) { const int rb = wc * 64 + n * 16 + fr; Bt[n] = *reinterpret_cast<const bf16x8*>(SB + rb * 64 + ((fq ^ ((rb >> 2) & 3)) * 16)); }
; #pragma unroll
;     for (int m = 0; m < 8; ++m) { const int ra = wr * 128 + m * 16 + fr; At[m] = *reinterpret_cast<const bf16x8*>(SA + ra * 64 + ((fq ^ ((ra >> 2) & 3)) * 16)); }
;     if (i + 3 < nk) stage(i + 3);
; #pragma unroll
;     for (int m = 0; m < 8; ++m)
; #pragma unroll
;       for (int n = 0; n < 4; ++n) acc[m][n] = __builtin_amdgcn_mfma_f32_16x16x32_bf16(Bt[n], At[m], acc[m][n], 0, 0, 0);
;   }
;   __syncthreads();
	v_add3_u32 v252, v205, v147, s8
	v_add3_u32 v215, v205, v151, s8
	s_nop 0
	ds_read_b128 v[216:219], v252 offset:16384
	ds_read_b128 v[220:223], v252 offset:17408
	ds_read_b128 v[232:235], v252 offset:18432
	ds_read_b128 v[236:239], v252 offset:19456
	ds_read_b128 v[224:227], v215
	ds_read_b128 v[228:231], v215 offset:1024
	v_mfma_f32_16x16x32_bf16 v[28:31], v[180:183], v[240:243], v[28:31]
	v_mfma_f32_16x16x32_bf16 v[24:27], v[180:183], v[244:247], v[24:27]
	v_mfma_f32_16x16x32_bf16 v[20:23], v[180:183], v[248:251], v[20:23]
	v_mfma_f32_16x16x32_bf16 v[16:19], v[180:183], v[176:179], v[16:19]
	v_mfma_f32_16x16x32_bf16 v[12:15], v[210:213], v[240:243], v[12:15]
	v_mfma_f32_16x16x32_bf16 v[8:11], v[210:213], v[244:247], v[8:11]
	v_mfma_f32_16x16x32_bf16 v[4:7], v[210:213], v[248:251], v[4:7]
	v_mfma_f32_16x16x32_bf16 v[0:3], v[210:213], v[176:179], v[0:3]
	ds_read_b128 v[180:183], v215 offset:2048
	ds_read_b128 v[210:213], v215 offset:3072
	s_waitcnt lgkmcnt(2)
	v_mfma_f32_16x16x32_bf16 v[124:127], v[224:227], v[216:219], v[124:127]
	v_mfma_f32_16x16x32_bf16 v[120:123], v[224:227], v[220:223], v[120:123]
	v_mfma_f32_16x16x32_bf16 v[116:119], v[224:227], v[232:235], v[116:119]
	v_mfma_f32_16x16x32_bf16 v[112:115], v[224:227], v[236:239], v[112:115]
	v_mfma_f32_16x16x32_bf16 v[108:111], v[228:231], v[216:219], v[108:111]
	v_mfma_f32_16x16x32_bf16 v[104:107], v[228:231], v[220:223], v[104:107]
	v_mfma_f32_16x16x32_bf16 v[100:103], v[228:231], v[232:235], v[100:103]
	v_mfma_f32_16x16x32_bf16 v[96:99], v[228:231], v[236:239], v[96:99]
	ds_read_b128 v[224:227], v215 offset:4096
	ds_read_b128 v[228:231], v215 offset:5120
	s_waitcnt lgkmcnt(2)
	v_mfma_f32_16x16x32_bf16 v[92:95], v[180:183], v[216:219], v[92:95]
	v_mfma_f32_16x16x32_bf16 v[88:91], v[180:183], v[220:223], v[88:91]
	v_mfma_f32_16x16x32_bf16 v[84:87], v[180:183], v[232:235], v[84:87]
	v_mfma_f32_16x16x32_bf16 v[80:83], v[180:183], v[236:239], v[80:83]
	v_mfma_f32_16x16x32_bf16 v[76:79], v[210:213], v[216:219], v[76:79]
	v_mfma_f32_16x16x32_bf16 v[72:75], v[210:213], v[220:223], v[72:75]
	v_mfma_f32_16x16x32_bf16 v[68:71], v[210:213], v[232:235], v[68:71]
	v_mfma_f32_16x16x32_bf16 v[64:67], v[210:213], v[236:239], v[64:67]
	ds_read_b128 v[180:183], v215 offset:6144
	ds_read_b128 v[210:213], v215 offset:7168
	s_waitcnt lgkmcnt(2)
	v_mfma_f32_16x16x32_bf16 v[60:63], v[224:227], v[216:219], v[60:63]
	v_mfma_f32_16x16x32_bf16 v[56:59], v[224:227], v[220:223], v[56:59]
	v_mfma_f32_16x16x32_bf16 v[52:55], v[224:227], v[232:235], v[52:55]
	v_mfma_f32_16x16x32_bf16 v[48:51], v[224:227], v[236:239], v[48:51]
	v_mfma_f32_16x16x32_bf16 v[44:47], v[228:231], v[216:219], v[44:47]
	v_mfma_f32_16x16x32_bf16 v[40:43], v[228:231], v[220:223], v[40:43]
	v_mfma_f32_16x16x32_bf16 v[36:39], v[228:231], v[232:235], v[36:39]
	v_mfma_f32_16x16x32_bf16 v[32:35], v[228:231], v[236:239], v[32:35]
	s_add_i32 s8, s8, 0x8000
	s_and_b32 s8, s8, 0x18000
	s_waitcnt vmcnt(0) lgkmcnt(0)
	s_barrier
	v_add3_u32 v252, v205, v147, s8
	v_add3_u32 v215, v205, v151, s8
	s_nop 0
	ds_read_b128 v[240:243], v252 offset:16384
	ds_read_b128 v[244:247], v252 offset:17408
	ds_read_b128 v[248:251], v252 offset:18432
	ds_read_b128 v[176:179], v252 offset:19456
	ds_read_b128 v[224:227], v215
	ds_read_b128 v[228:231], v215 offset:1024
	v_mfma_f32_16x16x32_bf16 v[28:31], v[180:183], v[216:219], v[28:31]
	v_mfma_f32_16x16x32_bf16 v[24:27], v[180:183], v[220:223], v[24:27]
	v_mfma_f32_16x16x32_bf16 v[20:23], v[180:183], v[232:235], v[20:23]
	v_mfma_f32_16x16x32_bf16 v[16:19], v[180:183], v[236:239], v[16:19]
	v_mfma_f32_16x16x32_bf16 v[12:15], v[210:213], v[216:219], v[12:15]
	v_mfma_f32_16x16x32_bf16 v[8:11], v[210:213], v[220:223], v[8:11]
	v_mfma_f32_16x16x32_bf16 v[4:7], v[210:213], v[232:235], v[4:7]
	v_mfma_f32_16x16x32_bf16 v[0:3], v[210:213], v[236:239], v[0:3]
	ds_read_b128 v[180:183], v215 offset:2048
	ds_read_b128 v[210:213], v215 offset:3072
	s_waitcnt lgkmcnt(2)
	v_mfma_f32_16x16x32_bf16 v[124:127], v[224:227], v[240:243], v[124:127]
	v_mfma_f32_16x16x32_bf16 v[120:123], v[224:227], v[244:247], v[120:123]
	v_mfma_f32_16x16x32_bf16 v[116:119], v[224:227], v[248:251], v[116:119]
	v_mfma_f32_16x16x32_bf16 v[112:115], v[224:227], v[176:179], v[112:115]
	v_mfma_f32_16x16x32_bf16 v[108:111], v[228:231], v[240:243], v[108:111]
	v_mfma_f32_16x16x32_bf16 v[104:107], v[228:231], v[244:247], v[104:107]
	v_mfma_f32_16x16x32_bf16 v[100:103], v[228:231], v[248:251], v[100:103]
	v_mfma_f32_16x16x32_bf16 v[96:99], v[228:231], v[176:179], v[96:99]
	ds_read_b128 v[224:227], v215 offset:4096
	ds_read_b128 v[228:231], v215 offset:5120
	s_waitcnt lgkmcnt(2)
	v_mfma_f32_16x16x32_bf16 v[92:95], v[180:183], v[240:243], v[92:95]
	v_mfma_f32_16x16x32_bf16 v[88:91], v[180:183], v[244:247], v[88:91]
	v_mfma_f32_16x16x32_bf16 v[84:87], v[180:183], v[248:251], v[84:87]
	v_mfma_f32_16x16x32_bf16 v[80:83], v[180:183], v[176:179], v[80:83]
	v_mfma_f32_16x16x32_bf16 v[76:79], v[210:213], v[240:243], v[76:79]
	v_mfma_f32_16x16x32_bf16 v[72:75], v[210:213], v[244:247], v[72:75]
	v_mfma_f32_16x16x32_bf16 v[68:71], v[210:213], v[248:251], v[68:71]
	v_mfma_f32_16x16x32_bf16 v[64:67], v[210:213], v[176:179], v[64:67]
	ds_read_b128 v[180:183], v215 offset:6144
	ds_read_b128 v[210:213], v215 offset:7168
	s_waitcnt lgkmcnt(2)
	v_mfma_f32_16x16x32_bf16 v[60:63], v[224:227], v[240:243], v[60:63]
	v_mfma_f32_16x16x32_bf16 v[56:59], v[224:227], v[244:247], v[56:59]
	v_mfma_f32_16x16x32_bf16 v[52:55], v[224:227], v[248:251], v[52:55]
	v_mfma_f32_16x16x32_bf16 v[48:51], v[224:227], v[176:179], v[48:51]
	v_mfma_f32_16x16x32_bf16 v[44:47], v[228:231], v[240:243], v[44:47]
	v_mfma_f32_16x16x32_bf16 v[40:43], v[228:231], v[244:247], v[40:43]
	v_mfma_f32_16x16x32_bf16 v[36:39], v[228:231], v[248:251], v[36:39]
	v_mfma_f32_16x16x32_bf16 v[32:35], v[228:231], v[176:179], v[32:35]
	s_waitcnt lgkmcnt(0)
	v_mfma_f32_16x16x32_bf16 v[28:31], v[180:183], v[240:243], v[28:31]
	v_mfma_f32_16x16x32_bf16 v[24:27], v[180:183], v[244:247], v[24:27]
	v_mfma_f32_16x16x32_bf16 v[20:23], v[180:183], v[248:251], v[20:23]
	v_mfma_f32_16x16x32_bf16 v[16:19], v[180:183], v[176:179], v[16:19]
	v_mfma_f32_16x16x32_bf16 v[12:15], v[210:213], v[240:243], v[12:15]
	v_mfma_f32_16x16x32_bf16 v[8:11], v[210:213], v[244:247], v[8:11]
	v_mfma_f32_16x16x32_bf16 v[4:7], v[210:213], v[248:251], v[4:7]
	v_mfma_f32_16x16x32_bf16 v[0:3], v[210:213], v[176:179], v[0:3]
	s_nop 7
	s_nop 3
	s_waitcnt vmcnt(0) lgkmcnt(0)
	s_barrier
; DI u16 f2bf(float x) { return (u16)(pack2bf(x, 0.f) & 0xffffu); }
; template <class Epi>
; DI void gemm_tile256(const u16* __restrict__ Ag, long lda, const u16* __restrict__ Bg, long ldb, int nk, char* shm, Epi&& epi) {
;     ...
;   for (int m = 0; m < 8; ++m)
; #pragma unroll
;     for (int n = 0; n < 4; ++n) epi(wr * 128 + m * 16 + fr, wc * 64 + n * 16 + fq * 4, acc[m][n]);
; DI void phase1(const Params& P, char* smem) {
;     ...
;         const int hd = c - 1536, b = r >> 13, l = r & 8191;
; #pragma unroll
;         for (int j = 0; j < 4; ++j) Vt[((long)(b * 512 + hd + j)) * 8192 + l] = f2bf(v[j]);
	v_lshrrev_b32_e32 v224, 4, v208
	v_and_b32_e32 v225, 15, v208
	v_lshlrev_b32_e32 v226, 2, v224
	v_sub_u32_e32 v228, v155, v226
	s_lshr_b32 s6, s30, 13
	s_lshl_b32 s6, s6, 9
	v_add3_u32 v228, v228, v225, s6
	v_mov_b32_e32 v229, 0
	s_and_b32 s7, s30, 0x1fff
	v_sub_u32_e32 v230, v153, v225
	v_add3_u32 v230, v230, v226, s7
	v_mov_b32_e32 v231, 0
	v_lshlrev_b64 v[216:217], 14, v[228:229]
	v_lshl_add_u64 v[216:217], v[216:217], 0, s[62:63]
	v_lshl_add_u64 v[216:217], v[230:231], 1, v[216:217]
	s_mov_b32 s6, 0x40000
	s_mov_b32 s7, 0
	v_lshl_add_u64 v[218:219], v[216:217], 0, s[6:7]
	v_lshl_add_u64 v[220:221], v[218:219], 0, s[6:7]
	v_lshl_add_u64 v[222:223], v[220:221], 0, s[6:7]
	v_cvt_pk_bf16_f32 v124, v124, v125
	v_cvt_pk_bf16_f32 v125, v126, v127
	global_store_dwordx2 v[216:217], v[124:125], off offset:0
	v_cvt_pk_bf16_f32 v120, v120, v121
	v_cvt_pk_bf16_f32 v121, v122, v123
	global_store_dwordx2 v[218:219], v[120:121], off offset:0
	v_cvt_pk_bf16_f32 v116, v116, v117
	v_cvt_pk_bf16_f32 v117, v118, v119
	global_store_dwordx2 v[220:221], v[116:117], off offset:0
	v_cvt_pk_bf16_f32 v112, v112, v113
	v_cvt_pk_bf16_f32 v113, v114, v115
	global_store_dwordx2 v[222:223], v[112:113], off offset:0
	v_cvt_pk_bf16_f32 v108, v108, v109
	v_cvt_pk_bf16_f32 v109, v110, v111
	global_store_dwordx2 v[216:217], v[108:109], off offset:32
	v_cvt_pk_bf16_f32 v104, v104, v105
	v_cvt_pk_bf16_f32 v105, v106, v107
	global_store_dwordx2 v[218:219], v[104:105], off offset:32
	v_cvt_pk_bf16_f32 v100, v100, v101
	v_cvt_pk_bf16_f32 v101, v102, v103
	global_store_dwordx2 v[220:221], v[100:101], off offset:32
	v_cvt_pk_bf16_f32 v96, v96, v97
	v_cvt_pk_bf16_f32 v97, v98, v99
	global_store_dwordx2 v[222:223], v[96:97], off offset:32
	v_cvt_pk_bf16_f32 v92, v92, v93
	v_cvt_pk_bf16_f32 v93, v94, v95
	global_store_dwordx2 v[216:217], v[92:93], off offset:64
	v_cvt_pk_bf16_f32 v88, v88, v89
	v_cvt_pk_bf16_f32 v89, v90, v91
	global_store_dwordx2 v[218:219], v[88:89], off offset:64
	v_cvt_pk_bf16_f32 v84, v84, v85
	v_cvt_pk_bf16_f32 v85, v86, v87
	global_store_dwordx2 v[220:221], v[84:85], off offset:64
	v_cvt_pk_bf16_f32 v80, v80, v81
	v_cvt_pk_bf16_f32 v81, v82, v83
	global_store_dwordx2 v[222:223], v[80:81], off offset:64
	v_cvt_pk_bf16_f32 v76, v76, v77
	v_cvt_pk_bf16_f32 v77, v78, v79
	global_store_dwordx2 v[216:217], v[76:77], off offset:96
	v_cvt_pk_bf16_f32 v72, v72, v73
	v_cvt_pk_bf16_f32 v73, v74, v75
	global_store_dwordx2 v[218:219], v[72:73], off offset:96
	v_cvt_pk_bf16_f32 v68, v68, v69
	v_cvt_pk_bf16_f32 v69, v70, v71
	global_store_dwordx2 v[220:221], v[68:69], off offset:96
	v_cvt_pk_bf16_f32 v64, v64, v65
	v_cvt_pk_bf16_f32 v65, v66, v67
	global_store_dwordx2 v[222:223], v[64:65], off offset:96
	v_cvt_pk_bf16_f32 v60, v60, v61
	v_cvt_pk_bf16_f32 v61, v62, v63
	global_store_dwordx2 v[216:217], v[60:61], off offset:128
	v_cvt_pk_bf16_f32 v56, v56, v57
	v_cvt_pk_bf16_f32 v57, v58, v59
	global_store_dwordx2 v[218:219], v[56:57], off offset:128
	v_cvt_pk_bf16_f32 v52, v52, v53
	v_cvt_pk_bf16_f32 v53, v54, v55
	global_store_dwordx2 v[220:221], v[52:53], off offset:128
	v_cvt_pk_bf16_f32 v48, v48, v49
	v_cvt_pk_bf16_f32 v49, v50, v51
	global_store_dwordx2 v[222:223], v[48:49], off offset:128
	v_cvt_pk_bf16_f32 v44, v44, v45
	v_cvt_pk_bf16_f32 v45, v46, v47
	global_store_dwordx2 v[216:217], v[44:45], off offset:160
	v_cvt_pk_bf16_f32 v40, v40, v41
	v_cvt_pk_bf16_f32 v41, v42, v43
	global_store_dwordx2 v[218:219], v[40:41], off offset:160
	v_cvt_pk_bf16_f32 v36, v36, v37
	v_cvt_pk_bf16_f32 v37, v38, v39
	global_store_dwordx2 v[220:221], v[36:37], off offset:160
	v_cvt_pk_bf16_f32 v32, v32, v33
	v_cvt_pk_bf16_f32 v33, v34, v35
	global_store_dwordx2 v[222:223], v[32:33], off offset:160
	v_cvt_pk_bf16_f32 v28, v28, v29
	v_cvt_pk_bf16_f32 v29, v30, v31
	global_store_dwordx2 v[216:217], v[28:29], off offset:192
	v_cvt_pk_bf16_f32 v24, v24, v25
	v_cvt_pk_bf16_f32 v25, v26, v27
	global_store_dwordx2 v[218:219], v[24:25], off offset:192
	v_cvt_pk_bf16_f32 v20, v20, v21
	v_cvt_pk_bf16_f32 v21, v22, v23
	global_store_dwordx2 v[220:221], v[20:21], off offset:192
	v_cvt_pk_bf16_f32 v16, v16, v17
	v_cvt_pk_bf16_f32 v17, v18, v19
	global_store_dwordx2 v[222:223], v[16:17], off offset:192
	v_cvt_pk_bf16_f32 v12, v12, v13
	v_cvt_pk_bf16_f32 v13, v14, v15
	global_store_dwordx2 v[216:217], v[12:13], off offset:224
	v_cvt_pk_bf16_f32 v8, v8, v9
	v_cvt_pk_bf16_f32 v9, v10, v11
	global_store_dwordx2 v[218:219], v[8:9], off offset:224
	v_cvt_pk_bf16_f32 v4, v4, v5
	v_cvt_pk_bf16_f32 v5, v6, v7
	global_store_dwordx2 v[220:221], v[4:5], off offset:224
	v_cvt_pk_bf16_f32 v0, v0, v1
	v_cvt_pk_bf16_f32 v1, v2, v3
	global_store_dwordx2 v[222:223], v[0:1], off offset:224
	v_or_b32_e32 v212, 0x50, v153
	v_or_b32_e32 v213, 0x60, v153
	s_branch .LBB0_106
.Lgemm_p1_n:
	s_waitcnt vmcnt(8)
	s_barrier
	v_add3_u32 v252, v205, v147, s8
	v_add3_u32 v215, v205, v151, s8
	s_nop 0
	ds_read_b128 v[216:219], v252 offset:16384
	ds_read_b128 v[220:223], v252 offset:17408
	ds_read_b128 v[232:235], v252 offset:18432
	ds_read_b128 v[236:239], v252 offset:19456
	ds_read_b128 v[224:227], v215
	ds_read_b128 v[228:231], v215 offset:1024

; template <class Epi>
; DI void gemm_tile256(const u16* __restrict__ Ag, long lda, const u16* __restrict__ Bg, long ldb, int nk, char* shm, Epi&& epi) {
;     ...
;   __syncthreads();
; #pragma unroll
;   for (int m = 0; m < 8; ++m)
; #pragma unroll
;     for (int n = 0; n < 4; ++n) epi(wr * 128 + m * 16 + fr, wc * 64 + n * 16 + fq * 4, acc[m][n]);
; DI void phase6(const Params& P, char* smem) {
;     ...
;     gemm_tile256(cat + (long)brow * 1024, 1024, WoT + (long)bcol * 1024, 1024, 32, smem, [&](int row, int col0, f32x4 v) {
;       const long o = (long)(brow + row) * 1024 + bcol + col0;
;       const float4 xs = *reinterpret_cast<const float4*>(P.x + o);
;       *reinterpret_cast<float4*>(Z1 + o) = make_float4(ALPHA * xs.x + v[0], ALPHA * xs.y + v[1], ALPHA * xs.z + v[2], ALPHA * xs.w + v[3]);
;     });
.Lgemm_p6_kend:
	s_nop 7
	s_nop 3
	s_add_i32 s15, s15, s9
	s_add_i32 s4, s4, s14
	s_cmp_lt_i32 s15, 64
	s_waitcnt vmcnt(0) lgkmcnt(0)
	s_barrier
	v_add_u32_e32 v164, s10, v155
	v_ashrrev_i32_e32 v165, 31, v164
	v_lshlrev_b64 v[196:197], 10, v[164:165]
	v_or_b32_e32 v164, v196, v148
	v_mov_b32_e32 v165, v197
	v_lshlrev_b64 v[164:165], 2, v[164:165]
	v_lshl_add_u64 v[198:199], s[52:53], 0, v[164:165]
	v_lshl_add_u64 v[200:201], s[38:39], 0, v[164:165]
	global_load_dwordx4 v[164:167], v[198:199], off
	s_waitcnt vmcnt(0)
	s_nop 4
	v_pk_fma_f32 v[124:125], v[164:165], s[6:7], v[124:125] op_sel_hi:[1,0,1]
	v_pk_fma_f32 v[126:127], v[166:167], s[6:7], v[126:127] op_sel_hi:[1,0,1]
	global_store_dwordx4 v[200:201], v[124:127], off
	s_nop 0
	v_or_b32_e32 v124, v196, v150
	v_mov_b32_e32 v125, v197
	v_lshl_add_u64 v[164:165], v[124:125], 2, s[38:39]
	global_load_dwordx4 v[124:127], v[198:199], off offset:64
	s_waitcnt vmcnt(0)
	v_pk_fma_f32 v[120:121], v[124:125], s[6:7], v[120:121] op_sel_hi:[1,0,1]
	v_pk_fma_f32 v[122:123], v[126:127], s[6:7], v[122:123] op_sel_hi:[1,0,1]
	global_store_dwordx4 v[164:165], v[120:123], off
	s_nop 0
	v_or_b32_e32 v120, v196, v152
	v_mov_b32_e32 v121, v197
	v_lshl_add_u64 v[124:125], v[120:121], 2, s[38:39]
	global_load_dwordx4 v[120:123], v[198:199], off offset:128
	v_or_b32_e32 v196, v196, v154
	s_waitcnt vmcnt(0)
	v_pk_fma_f32 v[116:117], v[120:121], s[6:7], v[116:117] op_sel_hi:[1,0,1]
	v_pk_fma_f32 v[118:119], v[122:123], s[6:7], v[118:119] op_sel_hi:[1,0,1]
	global_store_dwordx4 v[124:125], v[116:119], off
	global_load_dwordx4 v[116:119], v[198:199], off offset:192
	v_lshl_add_u64 v[120:121], v[196:197], 2, s[38:39]
	s_waitcnt vmcnt(0)
	v_pk_fma_f32 v[112:113], v[116:117], s[6:7], v[112:113] op_sel_hi:[1,0,1]
	v_pk_fma_f32 v[114:115], v[118:119], s[6:7], v[114:115] op_sel_hi:[1,0,1]
	global_store_dwordx4 v[120:121], v[112:115], off
	s_nop 0
	v_add_u32_e32 v112, s10, v176
	v_ashrrev_i32_e32 v113, 31, v112
	v_lshlrev_b64 v[116:117], 10, v[112:113]
	v_or_b32_e32 v112, v116, v148
	v_mov_b32_e32 v113, v117
	v_lshlrev_b64 v[112:113], 2, v[112:113]
	v_lshl_add_u64 v[118:119], s[52:53], 0, v[112:113]
	v_lshl_add_u64 v[120:121], s[38:39], 0, v[112:113]
	global_load_dwordx4 v[112:115], v[118:119], off
	s_waitcnt vmcnt(0)
	v_pk_fma_f32 v[108:109], v[112:113], s[6:7], v[108:109] op_sel_hi:[1,0,1]
	v_pk_fma_f32 v[110:111], v[114:115], s[6:7], v[110:111] op_sel_hi:[1,0,1]
	global_store_dwordx4 v[120:121], v[108:111], off
	s_nop 0
	v_or_b32_e32 v108, v116, v150
	v_mov_b32_e32 v109, v117
	v_lshl_add_u64 v[112:113], v[108:109], 2, s[38:39]
	global_load_dwordx4 v[108:111], v[118:119], off offset:64
	s_waitcnt vmcnt(0)
	v_pk_fma_f32 v[104:105], v[108:109], s[6:7], v[104:105] op_sel_hi:[1,0,1]
	v_pk_fma_f32 v[106:107], v[110:111], s[6:7], v[106:107] op_sel_hi:[1,0,1]
	global_store_dwordx4 v[112:113], v[104:107], off
	s_nop 0
	v_or_b32_e32 v104, v116, v152
	v_mov_b32_e32 v105, v117
	v_lshl_add_u64 v[108:109], v[104:105], 2, s[38:39]
	global_load_dwordx4 v[104:107], v[118:119], off offset:128
	v_or_b32_e32 v116, v116, v154
	s_waitcnt vmcnt(0)
	v_pk_fma_f32 v[100:101], v[104:105], s[6:7], v[100:101] op_sel_hi:[1,0,1]
	v_pk_fma_f32 v[102:103], v[106:107], s[6:7], v[102:103] op_sel_hi:[1,0,1]
	global_store_dwordx4 v[108:109], v[100:103], off
	global_load_dwordx4 v[100:103], v[118:119], off offset:192
	v_lshl_add_u64 v[104:105], v[116:117], 2, s[38:39]
	s_waitcnt vmcnt(0)
	v_pk_fma_f32 v[96:97], v[100:101], s[6:7], v[96:97] op_sel_hi:[1,0,1]
	v_pk_fma_f32 v[98:99], v[102:103], s[6:7], v[98:99] op_sel_hi:[1,0,1]
	global_store_dwordx4 v[104:105], v[96:99], off
	s_nop 0
	v_add_u32_e32 v96, s10, v177
	v_ashrrev_i32_e32 v97, 31, v96
	v_lshlrev_b64 v[100:101], 10, v[96:97]
	v_or_b32_e32 v96, v100, v148
	v_mov_b32_e32 v97, v101
	v_lshlrev_b64 v[96:97], 2, v[96:97]
	v_lshl_add_u64 v[102:103], s[52:53], 0, v[96:97]
	v_lshl_add_u64 v[104:105], s[38:39], 0, v[96:97]
	global_load_dwordx4 v[96:99], v[102:103], off
	s_waitcnt vmcnt(0)
	v_pk_fma_f32 v[92:93], v[96:97], s[6:7], v[92:93] op_sel_hi:[1,0,1]
	v_pk_fma_f32 v[94:95], v[98:99], s[6:7], v[94:95] op_sel_hi:[1,0,1]
	global_store_dwordx4 v[104:105], v[92:95], off
	s_nop 0
	v_or_b32_e32 v92, v100, v150
	v_mov_b32_e32 v93, v101
	v_lshl_add_u64 v[96:97], v[92:93], 2, s[38:39]
	global_load_dwordx4 v[92:95], v[102:103], off offset:64
	s_waitcnt vmcnt(0)
	v_pk_fma_f32 v[88:89], v[92:93], s[6:7], v[88:89] op_sel_hi:[1,0,1]
	v_pk_fma_f32 v[90:91], v[94:95], s[6:7], v[90:91] op_sel_hi:[1,0,1]
	global_store_dwordx4 v[96:97], v[88:91], off
	s_nop 0
	v_or_b32_e32 v88, v100, v152
	v_mov_b32_e32 v89, v101
	v_lshl_add_u64 v[92:93], v[88:89], 2, s[38:39]
	global_load_dwordx4 v[88:91], v[102:103], off offset:128
	v_or_b32_e32 v100, v100, v154
	s_waitcnt vmcnt(0)
	v_pk_fma_f32 v[84:85], v[88:89], s[6:7], v[84:85] op_sel_hi:[1,0,1]
	v_pk_fma_f32 v[86:87], v[90:91], s[6:7], v[86:87] op_sel_hi:[1,0,1]
	global_store_dwordx4 v[92:93], v[84:87], off
	global_load_dwordx4 v[84:87], v[102:103], off offset:192
	v_lshl_add_u64 v[88:89], v[100:101], 2, s[38:39]
	s_waitcnt vmcnt(0)
	v_pk_fma_f32 v[80:81], v[84:85], s[6:7], v[80:81] op_sel_hi:[1,0,1]
	v_pk_fma_f32 v[82:83], v[86:87], s[6:7], v[82:83] op_sel_hi:[1,0,1]
	global_store_dwordx4 v[88:89], v[80:83], off
	s_nop 1
	v_add_u32_e32 v80, s10, v178
	v_ashrrev_i32_e32 v81, 31, v80
	v_lshlrev_b64 v[84:85], 10, v[80:81]
	v_or_b32_e32 v80, v84, v148
	v_mov_b32_e32 v81, v85
	v_lshlrev_b64 v[80:81], 2, v[80:81]
	v_lshl_add_u64 v[86:87], s[52:53], 0, v[80:81]
	v_lshl_add_u64 v[88:89], s[38:39], 0, v[80:81]
	global_load_dwordx4 v[80:83], v[86:87], off
	s_waitcnt vmcnt(0)
; template <class Epi>
; DI void gemm_tile256(const u16* __restrict__ Ag, long lda, const u16* __restrict__ Bg, long ldb, int nk, char* shm, Epi&& epi) {
;     ...
;   for (int m = 0; m < 8; ++m)
; #pragma unroll
;     for (int n = 0; n < 4; ++n) epi(wr * 128 + m * 16 + fr, wc * 64 + n * 16 + fq * 4, acc[m][n]);
; DI void phase6(const Params& P, char* smem) {
;     ...
;       const long o = (long)(brow + row) * 1024 + bcol + col0;
;       const float4 xs = *reinterpret_cast<const float4*>(P.x + o);
;       *reinterpret_cast<float4*>(Z1 + o) = make_float4(ALPHA * xs.x + v[0], ALPHA * xs.y + v[1], ALPHA * xs.z + v[2], ALPHA * xs.w + v[3]);
;     });
	v_pk_fma_f32 v[76:77], v[80:81], s[6:7], v[76:77] op_sel_hi:[1,0,1]
	v_pk_fma_f32 v[78:79], v[82:83], s[6:7], v[78:79] op_sel_hi:[1,0,1]
	global_store_dwordx4 v[88:89], v[76:79], off
	s_nop 1
	v_or_b32_e32 v76, v84, v150
	v_mov_b32_e32 v77, v85
	v_lshl_add_u64 v[80:81], v[76:77], 2, s[38:39]
	global_load_dwordx4 v[76:79], v[86:87], off offset:64
	s_waitcnt vmcnt(0)
	v_pk_fma_f32 v[72:73], v[76:77], s[6:7], v[72:73] op_sel_hi:[1,0,1]
	v_pk_fma_f32 v[74:75], v[78:79], s[6:7], v[74:75] op_sel_hi:[1,0,1]
	global_store_dwordx4 v[80:81], v[72:75], off
	s_nop 1
	v_or_b32_e32 v72, v84, v152
	v_mov_b32_e32 v73, v85
	v_lshl_add_u64 v[76:77], v[72:73], 2, s[38:39]
	global_load_dwordx4 v[72:75], v[86:87], off offset:128
	v_or_b32_e32 v84, v84, v154
	s_waitcnt vmcnt(0)
	v_pk_fma_f32 v[68:69], v[72:73], s[6:7], v[68:69] op_sel_hi:[1,0,1]
	v_pk_fma_f32 v[70:71], v[74:75], s[6:7], v[70:71] op_sel_hi:[1,0,1]
	global_store_dwordx4 v[76:77], v[68:71], off
	global_load_dwordx4 v[68:71], v[86:87], off offset:192
	v_lshl_add_u64 v[72:73], v[84:85], 2, s[38:39]
	s_waitcnt vmcnt(0)
	v_pk_fma_f32 v[64:65], v[68:69], s[6:7], v[64:65] op_sel_hi:[1,0,1]
	v_pk_fma_f32 v[66:67], v[70:71], s[6:7], v[66:67] op_sel_hi:[1,0,1]
	global_store_dwordx4 v[72:73], v[64:67], off
	s_nop 1
	v_add_u32_e32 v64, s10, v179
	v_ashrrev_i32_e32 v65, 31, v64
	v_lshlrev_b64 v[68:69], 10, v[64:65]
	v_or_b32_e32 v64, v68, v148
	v_mov_b32_e32 v65, v69
	v_lshlrev_b64 v[64:65], 2, v[64:65]
	v_lshl_add_u64 v[70:71], s[52:53], 0, v[64:65]
	v_lshl_add_u64 v[72:73], s[38:39], 0, v[64:65]
	global_load_dwordx4 v[64:67], v[70:71], off
	s_waitcnt vmcnt(0)
	v_pk_fma_f32 v[60:61], v[64:65], s[6:7], v[60:61] op_sel_hi:[1,0,1]
	v_pk_fma_f32 v[62:63], v[66:67], s[6:7], v[62:63] op_sel_hi:[1,0,1]
	global_store_dwordx4 v[72:73], v[60:63], off
	s_nop 1
	v_or_b32_e32 v60, v68, v150
	v_mov_b32_e32 v61, v69
	v_lshl_add_u64 v[64:65], v[60:61], 2, s[38:39]
	global_load_dwordx4 v[60:63], v[70:71], off offset:64
	s_waitcnt vmcnt(0)
	v_pk_fma_f32 v[56:57], v[60:61], s[6:7], v[56:57] op_sel_hi:[1,0,1]
	v_pk_fma_f32 v[58:59], v[62:63], s[6:7], v[58:59] op_sel_hi:[1,0,1]
	global_store_dwordx4 v[64:65], v[56:59], off
	s_nop 1
	v_or_b32_e32 v56, v68, v152
	v_mov_b32_e32 v57, v69
	v_lshl_add_u64 v[60:61], v[56:57], 2, s[38:39]
	global_load_dwordx4 v[56:59], v[70:71], off offset:128
	v_or_b32_e32 v68, v68, v154
	s_waitcnt vmcnt(0)
	v_pk_fma_f32 v[52:53], v[56:57], s[6:7], v[52:53] op_sel_hi:[1,0,1]
	v_pk_fma_f32 v[54:55], v[58:59], s[6:7], v[54:55] op_sel_hi:[1,0,1]
	global_store_dwordx4 v[60:61], v[52:55], off
	global_load_dwordx4 v[52:55], v[70:71], off offset:192
	v_lshl_add_u64 v[56:57], v[68:69], 2, s[38:39]
	s_waitcnt vmcnt(0)
	v_pk_fma_f32 v[48:49], v[52:53], s[6:7], v[48:49] op_sel_hi:[1,0,1]
	v_pk_fma_f32 v[50:51], v[54:55], s[6:7], v[50:51] op_sel_hi:[1,0,1]
	global_store_dwordx4 v[56:57], v[48:51], off
	s_nop 1
	v_add_u32_e32 v48, s10, v180
	v_ashrrev_i32_e32 v49, 31, v48
	v_lshlrev_b64 v[52:53], 10, v[48:49]
	v_or_b32_e32 v48, v52, v148
	v_mov_b32_e32 v49, v53
	v_lshlrev_b64 v[48:49], 2, v[48:49]
	v_lshl_add_u64 v[54:55], s[52:53], 0, v[48:49]
	v_lshl_add_u64 v[56:57], s[38:39], 0, v[48:49]
	global_load_dwordx4 v[48:51], v[54:55], off
	s_waitcnt vmcnt(0)
	v_pk_fma_f32 v[44:45], v[48:49], s[6:7], v[44:45] op_sel_hi:[1,0,1]
	v_pk_fma_f32 v[46:47], v[50:51], s[6:7], v[46:47] op_sel_hi:[1,0,1]
	global_store_dwordx4 v[56:57], v[44:47], off
	s_nop 1
	v_or_b32_e32 v44, v52, v150
	v_mov_b32_e32 v45, v53
	v_lshl_add_u64 v[48:49], v[44:45], 2, s[38:39]
	global_load_dwordx4 v[44:47], v[54:55], off offset:64
	s_waitcnt vmcnt(0)
	v_pk_fma_f32 v[40:41], v[44:45], s[6:7], v[40:41] op_sel_hi:[1,0,1]
	v_pk_fma_f32 v[42:43], v[46:47], s[6:7], v[42:43] op_sel_hi:[1,0,1]
	global_store_dwordx4 v[48:49], v[40:43], off
	s_nop 1
	v_or_b32_e32 v40, v52, v152
	v_mov_b32_e32 v41, v53
	v_lshl_add_u64 v[44:45], v[40:41], 2, s[38:39]
	global_load_dwordx4 v[40:43], v[54:55], off offset:128
	v_or_b32_e32 v52, v52, v154
	s_waitcnt vmcnt(0)
; template <class Epi>
; DI void gemm_tile256(const u16* __restrict__ Ag, long lda, const u16* __restrict__ Bg, long ldb, int nk, char* shm, Epi&& epi) {
;     ...
;   for (int m = 0; m < 8; ++m)
; #pragma unroll
;     for (int n = 0; n < 4; ++n) epi(wr * 128 + m * 16 + fr, wc * 64 + n * 16 + fq * 4, acc[m][n]);
; DI void phase6(const Params& P, char* smem) {
;     ...
;   for (int q = RBLK >> 3; q < 64; q += RGRID >> 3) {
;     const int brow = (q * 2 + ((RBLK & 7) >> 2)) * 256, bcol = (RBLK & 3) * 256;
;     gemm_tile256(cat + (long)brow * 1024, 1024, WoT + (long)bcol * 1024, 1024, 32, smem, [&](int row, int col0, f32x4 v) {
;       const long o = (long)(brow + row) * 1024 + bcol + col0;
;       const float4 xs = *reinterpret_cast<const float4*>(P.x + o);
;       *reinterpret_cast<float4*>(Z1 + o) = make_float4(ALPHA * xs.x + v[0], ALPHA * xs.y + v[1], ALPHA * xs.z + v[2], ALPHA * xs.w + v[3]);
;     });
	v_pk_fma_f32 v[36:37], v[40:41], s[6:7], v[36:37] op_sel_hi:[1,0,1]
	v_pk_fma_f32 v[38:39], v[42:43], s[6:7], v[38:39] op_sel_hi:[1,0,1]
	global_store_dwordx4 v[44:45], v[36:39], off
	global_load_dwordx4 v[36:39], v[54:55], off offset:192
	v_lshl_add_u64 v[40:41], v[52:53], 2, s[38:39]
	s_waitcnt vmcnt(0)
	v_pk_fma_f32 v[32:33], v[36:37], s[6:7], v[32:33] op_sel_hi:[1,0,1]
	v_pk_fma_f32 v[34:35], v[38:39], s[6:7], v[34:35] op_sel_hi:[1,0,1]
	global_store_dwordx4 v[40:41], v[32:35], off
	s_nop 1
	v_add_u32_e32 v32, s10, v181
	v_ashrrev_i32_e32 v33, 31, v32
	v_lshlrev_b64 v[36:37], 10, v[32:33]
	v_or_b32_e32 v32, v36, v148
	v_mov_b32_e32 v33, v37
	v_lshlrev_b64 v[32:33], 2, v[32:33]
	v_lshl_add_u64 v[38:39], s[52:53], 0, v[32:33]
	v_lshl_add_u64 v[40:41], s[38:39], 0, v[32:33]
	global_load_dwordx4 v[32:35], v[38:39], off
	s_waitcnt vmcnt(0)
	v_pk_fma_f32 v[28:29], v[32:33], s[6:7], v[28:29] op_sel_hi:[1,0,1]
	v_pk_fma_f32 v[30:31], v[34:35], s[6:7], v[30:31] op_sel_hi:[1,0,1]
	global_store_dwordx4 v[40:41], v[28:31], off
	s_nop 1
	v_or_b32_e32 v28, v36, v150
	v_mov_b32_e32 v29, v37
	v_lshl_add_u64 v[32:33], v[28:29], 2, s[38:39]
	global_load_dwordx4 v[28:31], v[38:39], off offset:64
	s_waitcnt vmcnt(0)
	v_pk_fma_f32 v[24:25], v[28:29], s[6:7], v[24:25] op_sel_hi:[1,0,1]
	v_pk_fma_f32 v[26:27], v[30:31], s[6:7], v[26:27] op_sel_hi:[1,0,1]
	global_store_dwordx4 v[32:33], v[24:27], off
	s_nop 1
	v_or_b32_e32 v24, v36, v152
	v_mov_b32_e32 v25, v37
	v_lshl_add_u64 v[28:29], v[24:25], 2, s[38:39]
	global_load_dwordx4 v[24:27], v[38:39], off offset:128
	v_or_b32_e32 v36, v36, v154
	s_waitcnt vmcnt(0)
	v_pk_fma_f32 v[20:21], v[24:25], s[6:7], v[20:21] op_sel_hi:[1,0,1]
	v_pk_fma_f32 v[22:23], v[26:27], s[6:7], v[22:23] op_sel_hi:[1,0,1]
	global_store_dwordx4 v[28:29], v[20:23], off
	global_load_dwordx4 v[20:23], v[38:39], off offset:192
	v_lshl_add_u64 v[24:25], v[36:37], 2, s[38:39]
	s_waitcnt vmcnt(0)
	v_pk_fma_f32 v[16:17], v[20:21], s[6:7], v[16:17] op_sel_hi:[1,0,1]
	v_pk_fma_f32 v[18:19], v[22:23], s[6:7], v[18:19] op_sel_hi:[1,0,1]
	global_store_dwordx4 v[24:25], v[16:19], off
	s_nop 1
	v_add_u32_e32 v16, s10, v182
	v_ashrrev_i32_e32 v17, 31, v16
	v_lshlrev_b64 v[20:21], 10, v[16:17]
	v_or_b32_e32 v16, v20, v148
	v_mov_b32_e32 v17, v21
	v_lshlrev_b64 v[16:17], 2, v[16:17]
	v_lshl_add_u64 v[22:23], s[52:53], 0, v[16:17]
	v_lshl_add_u64 v[24:25], s[38:39], 0, v[16:17]
	global_load_dwordx4 v[16:19], v[22:23], off
	s_waitcnt vmcnt(0)
	v_pk_fma_f32 v[12:13], v[16:17], s[6:7], v[12:13] op_sel_hi:[1,0,1]
	v_pk_fma_f32 v[14:15], v[18:19], s[6:7], v[14:15] op_sel_hi:[1,0,1]
	global_store_dwordx4 v[24:25], v[12:15], off
	s_nop 1
	v_or_b32_e32 v12, v20, v150
	v_mov_b32_e32 v13, v21
	v_lshl_add_u64 v[16:17], v[12:13], 2, s[38:39]
	global_load_dwordx4 v[12:15], v[22:23], off offset:64
	s_waitcnt vmcnt(0)
	v_pk_fma_f32 v[8:9], v[12:13], s[6:7], v[8:9] op_sel_hi:[1,0,1]
	v_pk_fma_f32 v[10:11], v[14:15], s[6:7], v[10:11] op_sel_hi:[1,0,1]
	global_store_dwordx4 v[16:17], v[8:11], off
	s_nop 1
	v_or_b32_e32 v8, v20, v152
	v_mov_b32_e32 v9, v21
	v_lshl_add_u64 v[12:13], v[8:9], 2, s[38:39]
	global_load_dwordx4 v[8:11], v[22:23], off offset:128
	v_or_b32_e32 v20, v20, v154
	s_waitcnt vmcnt(0)
	v_pk_fma_f32 v[4:5], v[8:9], s[6:7], v[4:5] op_sel_hi:[1,0,1]
	v_pk_fma_f32 v[6:7], v[10:11], s[6:7], v[6:7] op_sel_hi:[1,0,1]
	global_store_dwordx4 v[12:13], v[4:7], off
	global_load_dwordx4 v[4:7], v[22:23], off offset:192
	v_lshl_add_u64 v[8:9], v[20:21], 2, s[38:39]
	s_waitcnt vmcnt(0)
	v_pk_fma_f32 v[0:1], v[4:5], s[6:7], v[0:1] op_sel_hi:[1,0,1]
	v_pk_fma_f32 v[2:3], v[6:7], s[6:7], v[2:3] op_sel_hi:[1,0,1]
	global_store_dwordx4 v[8:9], v[0:3], off
	s_cbranch_scc1 .LBB0_946

; DI unsigned pack2bf(float a, float b) { const f2_t v = {a, b}; return __builtin_bit_cast(unsigned, __builtin_convertvector(v, bf2_t)); }
; template <class Epi>
; DI void gemm_tile256(const u16* __restrict__ Ag, long lda, const u16* __restrict__ Bg, long ldb, int nk, char* shm, Epi&& epi) {
;     ...
;   for (int m = 0; m < 8; ++m)
; #pragma unroll
;     for (int n = 0; n < 4; ++n) epi(wr * 128 + m * 16 + fr, wc * 64 + n * 16 + fq * 4, acc[m][n]);
; DI void phase8(const Params& P, char* smem) {
;     ...
;     gemm_tile256(h1b + (long)brow * 1024, 1024, WqT + (long)bcol * 1024, 1024, 32, smem, [&](int row, int col0, f32x4 v) {
;       *reinterpret_cast<uint2*>(Qp + (long)(brow + row) * 2048 + bcol + col0) = make_uint2(pack2bf(v[0], v[1]), pack2bf(v[2], v[3]));
;     });
.Lgemm_p8_kend:
	s_nop 7
	s_nop 3
	s_add_i32 s75, s75, s5
	s_add_i32 s6, s6, s8
	s_cmpk_lt_i32 s75, 0x80
	s_waitcnt vmcnt(0) lgkmcnt(0)
	s_barrier
	s_nop 6
	v_cvt_pk_bf16_f32 v124, v124, v125
	v_cvt_pk_bf16_f32 v125, v126, v127
	v_add_u32_e32 v126, s10, v165
	v_ashrrev_i32_e32 v127, 31, v126
	v_cvt_pk_bf16_f32 v108, v108, v109
	v_cvt_pk_bf16_f32 v109, v110, v111
	v_add_u32_e32 v110, s10, v166
	s_nop 2
	v_cvt_pk_bf16_f32 v92, v92, v93
	v_cvt_pk_bf16_f32 v93, v94, v95
	v_add_u32_e32 v94, s10, v167
	v_cvt_pk_bf16_f32 v76, v76, v77
	v_cvt_pk_bf16_f32 v77, v78, v79
	v_add_u32_e32 v78, s10, v176
	s_nop 2
	v_cvt_pk_bf16_f32 v60, v60, v61
	v_cvt_pk_bf16_f32 v61, v62, v63
	v_add_u32_e32 v62, s10, v177
	v_cvt_pk_bf16_f32 v44, v44, v45
	v_cvt_pk_bf16_f32 v45, v46, v47
	v_add_u32_e32 v46, s10, v178
	s_nop 2
	v_cvt_pk_bf16_f32 v28, v28, v29
	v_cvt_pk_bf16_f32 v29, v30, v31
	v_add_u32_e32 v30, s10, v179
	v_cvt_pk_bf16_f32 v12, v12, v13
	v_cvt_pk_bf16_f32 v13, v14, v15
	v_add_u32_e32 v14, s10, v180
	v_ashrrev_i32_e32 v111, 31, v110
	v_ashrrev_i32_e32 v95, 31, v94
	v_ashrrev_i32_e32 v79, 31, v78
	v_ashrrev_i32_e32 v63, 31, v62
	v_ashrrev_i32_e32 v47, 31, v46
	v_ashrrev_i32_e32 v31, 31, v30
	v_ashrrev_i32_e32 v15, 31, v14
	v_lshlrev_b64 v[126:127], 12, v[126:127]
	v_lshlrev_b64 v[110:111], 12, v[110:111]
	v_lshlrev_b64 v[94:95], 12, v[94:95]
	v_lshlrev_b64 v[78:79], 12, v[78:79]
	v_lshlrev_b64 v[62:63], 12, v[62:63]
	v_lshlrev_b64 v[46:47], 12, v[46:47]
	v_lshlrev_b64 v[30:31], 12, v[30:31]
	v_lshlrev_b64 v[14:15], 12, v[14:15]
	v_lshl_add_u64 v[126:127], v[148:149], 0, v[126:127]
	v_cvt_pk_bf16_f32 v120, v120, v121
	v_cvt_pk_bf16_f32 v121, v122, v123
	v_cvt_pk_bf16_f32 v116, v116, v117
	v_cvt_pk_bf16_f32 v117, v118, v119
	v_cvt_pk_bf16_f32 v112, v112, v113
	v_cvt_pk_bf16_f32 v113, v114, v115
	v_lshl_add_u64 v[110:111], v[148:149], 0, v[110:111]
	v_cvt_pk_bf16_f32 v104, v104, v105
	v_cvt_pk_bf16_f32 v105, v106, v107
	v_cvt_pk_bf16_f32 v100, v100, v101
	v_cvt_pk_bf16_f32 v101, v102, v103
	v_cvt_pk_bf16_f32 v96, v96, v97
	v_cvt_pk_bf16_f32 v97, v98, v99
	v_lshl_add_u64 v[94:95], v[148:149], 0, v[94:95]
	v_cvt_pk_bf16_f32 v88, v88, v89
	v_cvt_pk_bf16_f32 v89, v90, v91
	v_cvt_pk_bf16_f32 v84, v84, v85
	v_cvt_pk_bf16_f32 v85, v86, v87
	v_cvt_pk_bf16_f32 v80, v80, v81
	v_cvt_pk_bf16_f32 v81, v82, v83
	v_lshl_add_u64 v[78:79], v[148:149], 0, v[78:79]
	v_cvt_pk_bf16_f32 v72, v72, v73
	v_cvt_pk_bf16_f32 v73, v74, v75
	v_cvt_pk_bf16_f32 v68, v68, v69
	v_cvt_pk_bf16_f32 v69, v70, v71
	v_cvt_pk_bf16_f32 v64, v64, v65
	v_cvt_pk_bf16_f32 v65, v66, v67
	v_lshl_add_u64 v[62:63], v[148:149], 0, v[62:63]
	v_cvt_pk_bf16_f32 v56, v56, v57
	v_cvt_pk_bf16_f32 v57, v58, v59
	v_cvt_pk_bf16_f32 v52, v52, v53
	v_cvt_pk_bf16_f32 v53, v54, v55
	v_cvt_pk_bf16_f32 v48, v48, v49
	v_cvt_pk_bf16_f32 v49, v50, v51
	v_lshl_add_u64 v[46:47], v[148:149], 0, v[46:47]
	v_cvt_pk_bf16_f32 v40, v40, v41
	v_cvt_pk_bf16_f32 v41, v42, v43
	v_cvt_pk_bf16_f32 v36, v36, v37
	v_cvt_pk_bf16_f32 v37, v38, v39
	v_cvt_pk_bf16_f32 v32, v32, v33
	v_cvt_pk_bf16_f32 v33, v34, v35
	v_lshl_add_u64 v[30:31], v[148:149], 0, v[30:31]
	v_cvt_pk_bf16_f32 v24, v24, v25
	v_cvt_pk_bf16_f32 v25, v26, v27
	v_cvt_pk_bf16_f32 v20, v20, v21
	v_cvt_pk_bf16_f32 v21, v22, v23
	v_cvt_pk_bf16_f32 v16, v16, v17
	v_cvt_pk_bf16_f32 v17, v18, v19
	v_lshl_add_u64 v[14:15], v[148:149], 0, v[14:15]
	v_cvt_pk_bf16_f32 v8, v8, v9
	v_cvt_pk_bf16_f32 v9, v10, v11
	s_nop 1
	v_cvt_pk_bf16_f32 v4, v4, v5
	v_cvt_pk_bf16_f32 v5, v6, v7
	global_store_dwordx2 v[126:127], v[124:125], off
	s_nop 0
	v_cvt_pk_bf16_f32 v0, v0, v1
	v_cvt_pk_bf16_f32 v1, v2, v3
	global_store_dwordx2 v[126:127], v[120:121], off offset:32
	global_store_dwordx2 v[126:127], v[116:117], off offset:64
	global_store_dwordx2 v[126:127], v[112:113], off offset:96
	global_store_dwordx2 v[110:111], v[108:109], off
	global_store_dwordx2 v[110:111], v[104:105], off offset:32
	global_store_dwordx2 v[110:111], v[100:101], off offset:64
	global_store_dwordx2 v[110:111], v[96:97], off offset:96
	global_store_dwordx2 v[94:95], v[92:93], off
	global_store_dwordx2 v[94:95], v[88:89], off offset:32
	global_store_dwordx2 v[94:95], v[84:85], off offset:64
	global_store_dwordx2 v[94:95], v[80:81], off offset:96
	global_store_dwordx2 v[78:79], v[76:77], off
	global_store_dwordx2 v[78:79], v[72:73], off offset:32
	global_store_dwordx2 v[78:79], v[68:69], off offset:64
	global_store_dwordx2 v[78:79], v[64:65], off offset:96
	global_store_dwordx2 v[62:63], v[60:61], off
	global_store_dwordx2 v[62:63], v[56:57], off offset:32
	global_store_dwordx2 v[62:63], v[52:53], off offset:64
	global_store_dwordx2 v[62:63], v[48:49], off offset:96
	global_store_dwordx2 v[46:47], v[44:45], off
	global_store_dwordx2 v[46:47], v[40:41], off offset:32
	global_store_dwordx2 v[46:47], v[36:37], off offset:64
	global_store_dwordx2 v[46:47], v[32:33], off offset:96
	global_store_dwordx2 v[30:31], v[28:29], off
	global_store_dwordx2 v[30:31], v[24:25], off offset:32
	global_store_dwordx2 v[30:31], v[20:21], off offset:64
	global_store_dwordx2 v[30:31], v[16:17], off offset:96
	global_store_dwordx2 v[14:15], v[12:13], off
	global_store_dwordx2 v[14:15], v[8:9], off offset:32
	global_store_dwordx2 v[14:15], v[4:5], off offset:64
	global_store_dwordx2 v[14:15], v[0:1], off offset:96
	s_cbranch_scc1 .LBB0_1068
